# split barrier: workgroups post a global xa-done arrival at the xa->wo site; the LN1->gu site waits only for its row panel plus that (already complete) global count
# baseline (speedup 1.0000x reference)
.LBB0_226:
	s_getreg_b32 s0, hwreg(HW_REG_XCC_ID, 0, 4)
	s_and_b32 s9, s0, 15
	s_waitcnt vmcnt(0)
	s_waitcnt vmcnt(0)
	s_barrier
	s_and_saveexec_b64 s[0:1], s[52:53]
	v_readlane_b32 s24, v255, 22
	s_cbranch_execz .LBB0_278
	v_readlane_b32 s98, v253, 2
	v_readlane_b32 s99, v253, 3
	s_nop 0
	s_add_u32 s98, s98, 0x7c000
	s_addc_u32 s99, s99, 0
	s_and_b32 vcc_hi, s2, 7
	s_sub_u32 vcc_lo, 7, vcc_hi
	s_add_u32 vcc_lo, vcc_lo, s3
	s_lshr_b32 vcc_lo, vcc_lo, 3
	s_lshl_b32 vcc_hi, vcc_hi, 8
	s_add_u32 vcc_hi, vcc_hi, 0x8000
	s_cmp_lt_u32 s101, 8
	s_cselect_b32 m0, 0, 0x800
	s_add_u32 vcc_hi, vcc_hi, m0
	v_mov_b32_e32 v3, vcc_hi
	v_mov_b32_e32 v4, 1
	s_mov_b32 vcc_hi, vcc_lo
	s_waitcnt vmcnt(0) lgkmcnt(0)
	global_atomic_add v5, v3, v4, s[98:99] sc0
	s_waitcnt vmcnt(0)
	v_readfirstlane_b32 vcc_lo, v5
	s_add_i32 vcc_lo, vcc_lo, 1
	s_cmp_ge_u32 vcc_lo, vcc_hi
	s_cbranch_scc1 .Lb3_ok_1

.LBB0_954:
	s_getreg_b32 s0, hwreg(HW_REG_XCC_ID, 0, 4)
	s_and_b32 s10, s0, 15
	s_waitcnt vmcnt(0)
	s_barrier
	s_and_saveexec_b64 s[0:1], s[52:53]
	v_readlane_b32 s28, v255, 14
	v_readlane_b32 s14, v255, 16
	v_readlane_b32 s29, v255, 15
	v_readlane_b32 s15, v255, 17
	s_add_i32 s101, s101, 1
	s_cbranch_execz .LBB0_1006
	v_readlane_b32 s98, v253, 2
	v_readlane_b32 s99, v253, 3
	s_nop 0
	s_add_u32 s98, s98, 0x7c000
	s_addc_u32 s99, s99, 0
	s_and_b32 vcc_lo, s2, 63
	s_lshl_b32 vcc_lo, vcc_lo, 8
	s_add_u32 vcc_lo, vcc_lo, 0x2000
	v_mov_b32_e32 v3, vcc_lo
	v_mov_b32_e32 v4, 1
	s_lshl_b32 vcc_hi, s101, 2
	s_waitcnt vmcnt(0) lgkmcnt(0)
	global_atomic_add v5, v3, v4, s[98:99] sc0
	v_mov_b32_e32 v6, 0xa000
	global_atomic_add v6, v4, s[98:99]
	s_waitcnt vmcnt(0)
	v_readfirstlane_b32 vcc_lo, v5
	s_add_i32 vcc_lo, vcc_lo, 1
	s_cmp_ge_u32 vcc_lo, vcc_hi
	s_cbranch_scc1 .Lb3_ok_8

.LBB0_1067:
	s_getreg_b32 s0, hwreg(HW_REG_XCC_ID, 0, 4)
	s_and_b32 s10, s0, 15
	s_waitcnt vmcnt(0)
	s_barrier
	s_and_saveexec_b64 s[0:1], s[52:53]
	v_readlane_b32 s22, v255, 16
	v_readlane_b32 s23, v255, 17
	s_add_i32 s101, s101, 1
	s_cbranch_execz .LBB0_1119
	v_readlane_b32 s98, v253, 2
	v_readlane_b32 s99, v253, 3
	s_nop 0
	s_add_u32 s98, s98, 0x7c000
	s_addc_u32 s99, s99, 0
	s_and_b32 vcc_lo, s2, 63
	s_lshl_b32 vcc_lo, vcc_lo, 8
	s_add_u32 vcc_lo, vcc_lo, 0x2000
	v_mov_b32_e32 v3, vcc_lo
	v_mov_b32_e32 v4, 1
	s_lshl_b32 vcc_hi, s101, 2
	s_waitcnt vmcnt(0) lgkmcnt(0)
	global_atomic_add v5, v3, v4, s[98:99] sc0
	s_waitcnt vmcnt(0)
	v_readfirstlane_b32 vcc_lo, v5
	s_add_i32 vcc_lo, vcc_lo, 1
	s_cmp_ge_u32 vcc_lo, vcc_hi
	s_cbranch_scc1 .Lb3_ok_9

.Lb3_ok_9:
	s_add_i32 vcc_hi, s101, 1
	s_lshr_b32 vcc_hi, vcc_hi, 2
	s_mul_i32 vcc_hi, vcc_hi, s3
	v_mov_b32_e32 v6, 0xa000
	s_movk_i32 m0, 0x7fff
.Lb3_g_9:
	global_load_dword v5, v6, s[98:99] sc1
	s_waitcnt vmcnt(0)
	v_readfirstlane_b32 vcc_lo, v5
	s_cmp_ge_u32 vcc_lo, vcc_hi
	s_cbranch_scc1 .Lb3_gok_9
	s_sleep 1
	s_sub_u32 m0, m0, 1
	s_cmp_eq_u32 m0, 0
	s_cbranch_scc0 .Lb3_g_9
